# attention: dropped the agent-scope L1 invalidate at the intra-workgroup branch seams (producer and consumer waves share the CU's L1; barrier + vmcnt(0) kept)
# speedup vs baseline: 1.0185x; 1.0089x over previous
; __device__ __forceinline__ unsigned pk2(float lo, float hi) { return pg8::cvt_pk_bf16(lo, hi); }
; __device__ __forceinline__ void att_merge(f32x16& o0, f32x16& o1, float mrun, float lrun, int qpos, int brmode, bf16* OPh, float* MLh, bf16* outp, int h) {
;     ...
; #pragma unroll
;     for (int g = 0; g < 4; ++g) {
;         unsigned ax, ay, bx, by;
;         if (g < 2) { ax = pk2(o0[8 * g] * sc, o0[8 * g + 1] * sc); ay = pk2(o0[8 * g + 2] * sc, o0[8 * g + 3] * sc); bx = pk2(o0[8 * g + 4] * sc, o0[8 * g + 5] * sc); by = pk2(o0[8 * g + 6] * sc, o0[8 * g + 7] * sc); }
;         else { const int e = 8 * (g - 2); ax = pk2(o1[e] * sc, o1[e + 1] * sc); ay = pk2(o1[e + 2] * sc, o1[e + 3] * sc); bx = pk2(o1[e + 4] * sc, o1[e + 5] * sc); by = pk2(o1[e + 6] * sc, o1[e + 7] * sc); }
;         const auto rx = __builtin_amdgcn_permlane32_swap(ax, bx, false, false);
;         const auto ry = __builtin_amdgcn_permlane32_swap(ay, by, false, false);
;         gst<v4u>(dst + 16 * g, (v4u){rx[0], ry[0], rx[1], ry[1]});
;     }
; __device__ __forceinline__ void att_phase(unsigned char* ws, LAS unsigned char* lds, int lane, int wave, int G) {
;     ...
;         if (P.bar_after) { asm volatile("s_waitcnt vmcnt(0) lgkmcnt(0)" ::: "memory"); __syncthreads(); __builtin_amdgcn_fence(__ATOMIC_ACQUIRE, "agent"); }
.LBB0_114:
	v_pk_mul_f32 v[2:3], v[26:27], v[0:1] op_sel_hi:[1,0]
	v_pk_mul_f32 v[24:25], v[24:25], v[0:1] op_sel_hi:[1,0]
	v_pk_mul_f32 v[26:27], v[22:23], v[0:1] op_sel_hi:[1,0]
	v_pk_mul_f32 v[38:39], v[20:21], v[0:1] op_sel_hi:[1,0]
	v_cvt_pk_bf16_f32 v23, v2, v3
	v_cvt_pk_bf16_f32 v22, v24, v25
	v_cvt_pk_bf16_f32 v21, v26, v27
	v_cvt_pk_bf16_f32 v20, v38, v39
	v_lshl_add_u64 v[36:37], v[184:185], 1, v[42:43]
	s_nop 0
	v_permlane32_swap_b32_e32 v20, v22
	v_permlane32_swap_b32_e32 v21, v23
	v_pk_mul_f32 v[2:3], v[34:35], v[0:1] op_sel_hi:[1,0]
	global_store_dwordx4 v[36:37], v[20:23], off
	v_pk_mul_f32 v[8:9], v[8:9], v[0:1] op_sel_hi:[1,0]
	v_pk_mul_f32 v[6:7], v[6:7], v[0:1] op_sel_hi:[1,0]
	v_cvt_pk_bf16_f32 v23, v2, v3
	v_pk_mul_f32 v[2:3], v[10:11], v[0:1] op_sel_hi:[1,0]
	v_pk_mul_f32 v[10:11], v[4:5], v[0:1] op_sel_hi:[1,0]
	v_cvt_pk_bf16_f32 v5, v2, v3
	v_cvt_pk_bf16_f32 v4, v8, v9
	v_cvt_pk_bf16_f32 v3, v6, v7
	v_cvt_pk_bf16_f32 v2, v10, v11
	s_nop 1
	v_permlane32_swap_b32_e32 v2, v4
	v_permlane32_swap_b32_e32 v3, v5
	v_pk_mul_f32 v[20:21], v[32:33], v[0:1] op_sel_hi:[1,0]
	v_pk_mul_f32 v[24:25], v[30:31], v[0:1] op_sel_hi:[1,0]
	v_pk_mul_f32 v[26:27], v[28:29], v[0:1] op_sel_hi:[1,0]
	global_store_dwordx4 v[36:37], v[2:5], off offset:64
	v_pk_mul_f32 v[6:7], v[14:15], v[0:1] op_sel_hi:[1,0]
	v_pk_mul_f32 v[8:9], v[12:13], v[0:1] op_sel_hi:[1,0]
	v_pk_mul_f32 v[2:3], v[18:19], v[0:1] op_sel_hi:[1,0]
	v_pk_mul_f32 v[4:5], v[16:17], v[0:1] op_sel_hi:[1,0]
	v_cvt_pk_bf16_f32 v22, v20, v21
	v_cvt_pk_bf16_f32 v21, v24, v25
	v_cvt_pk_bf16_f32 v20, v26, v27
	v_cvt_pk_bf16_f32 v3, v2, v3
	v_cvt_pk_bf16_f32 v2, v4, v5
	v_cvt_pk_bf16_f32 v1, v6, v7
	v_cvt_pk_bf16_f32 v0, v8, v9
	v_cmp_ne_u32_e32 vcc, 0, v230
	v_permlane32_swap_b32_e32 v20, v22
	v_permlane32_swap_b32_e32 v21, v23
	v_permlane32_swap_b32_e32 v0, v2
	v_permlane32_swap_b32_e32 v1, v3
	global_store_dwordx4 v[36:37], v[20:23], off offset:32
	global_store_dwordx4 v[36:37], v[0:3], off offset:96
	s_cbranch_vccz .LBB0_60
	s_waitcnt vmcnt(0) lgkmcnt(0)
	s_barrier
	s_waitcnt vmcnt(0)
	s_branch .LBB0_60
